# v113 + per-tile software division in the FFN-up and W_in tile headers replaced by shift/mask (M-group size is always 8 for these shapes)
# speedup vs baseline: 1.0120x; 1.0051x over previous
;     __device__ bool next(int i, Unit& u) const { Unit t; if (!base.next(i >> 2, t)) return false; const int br = i & 3; u.pm = br * 64 + t.pm; u.pn = br * 4 + t.pn; return true; }
;     __host__ __device__ bool next(int i, Unit& u) const {
;         const long L = (long)i * G + c; if (L >= nwg) return false;
;         int wgid = (int)L; { const int q = nwg / NXCD, r = nwg % NXCD, xcd = wgid % NXCD, off = wgid / NXCD; wgid = (xcd < r ? xcd * (q + 1) : r * (q + 1) + (xcd - r) * q) + off; }
;         const int nig = WGM * nN, gid = wgid / nig, fm = gid * WGM, gsz = (nM - fm) < WGM ? (nM - fm) : WGM;
;         u.pm = fm + ((wgid % nig) % gsz); u.pn = (wgid % nig) / gsz; return true;
.LBB0_1127:
	s_add_i32 s1, s1, 1
	s_mul_i32 s2, s1, s39
	s_mul_hi_u32 s3, s1, s60
	s_add_i32 s3, s3, s2
	s_mul_i32 s2, s1, s60
	s_add_u32 s80, s2, s58
	s_addc_u32 s81, s3, s50
	v_mov_b64_e32 v[0:1], 0x600
	v_cmp_lt_i64_e64 s[2:3], s[80:81], v[0:1]
	v_mov_b64_e32 v[0:1], 0x5ff
	v_cmp_gt_i64_e32 vcc, s[80:81], v[0:1]
	s_cbranch_vccnz .LBB0_1129
	s_ashr_i32 s5, s80, 31
	s_lshr_b32 s5, s5, 29
	s_add_i32 s5, s80, s5
	s_ashr_i32 s9, s5, 3
	s_and_b32 s5, s5, -8
	s_sub_i32 s5, s80, s5
	s_cmp_lt_i32 s5, 0
	s_movk_i32 s22, 0xc1
	s_cselect_b32 s22, s22, 0xc0
	s_mul_i32 s5, s5, s22
	s_add_i32 s5, s5, s9
	s_mul_hi_i32 s9, s5, 0x2aaaaaab
	s_lshr_b32 s22, s9, 31
	s_ashr_i32 s9, s9, 5
	s_add_i32 s9, s9, s22
	s_lshl_b32 s22, s9, 3
	s_mulk_i32 s9, 0xc0
	s_sub_i32 s5, s5, s9
	s_lshr_b32 s76, s5, 3
	s_and_b32 s5, s5, 7
	s_add_i32 s78, s22, s5
	v_readlane_b32 s77, v255, 2
	s_and_b32 s77, s77, 7
	s_lshl_b32 s77, s77, 2
	s_add_i32 s76, s76, s77
	s_cmp_ge_u32 s76, 24
	s_cselect_b32 s77, 24, 0
	s_sub_i32 s76, s76, s77
	s_cmp_ge_u32 s76, 24
	s_cselect_b32 s77, 24, 0
	s_sub_i32 s76, s76, s77

;     __device__ bool next(int i, Unit& u) const { Unit t; if (!base.next(i >> 2, t)) return false; const int br = i & 3; u.pm = br * 64 + t.pm; u.pn = br * 4 + t.pn; return true; }
;     __host__ __device__ bool next(int i, Unit& u) const {
;         const long L = (long)i * G + c; if (L >= nwg) return false;
;         int wgid = (int)L; { const int q = nwg / NXCD, r = nwg % NXCD, xcd = wgid % NXCD, off = wgid / NXCD; wgid = (xcd < r ? xcd * (q + 1) : r * (q + 1) + (xcd - r) * q) + off; }
;         const int nig = WGM * nN, gid = wgid / nig, fm = gid * WGM, gsz = (nM - fm) < WGM ? (nM - fm) : WGM;
;         u.pm = fm + ((wgid % nig) % gsz); u.pn = (wgid % nig) / gsz; return true;
.LBB0_1353:
	s_add_i32 s59, s59, 1
	s_mul_i32 s2, s59, s57
	s_mul_hi_u32 s3, s59, s60
	s_add_i32 s3, s3, s2
	s_mul_i32 s2, s59, s60
	s_add_u32 s12, s2, s58
	s_addc_u32 s13, s3, s33
	v_mov_b64_e32 v[0:1], 0xb00
	v_cmp_lt_i64_e64 s[2:3], s[12:13], v[0:1]
	v_mov_b64_e32 v[0:1], 0xaff
	v_cmp_gt_i64_e32 vcc, s[12:13], v[0:1]
	s_cbranch_vccnz .LBB0_1355
	s_ashr_i32 s8, s12, 31
	s_lshr_b32 s8, s8, 29
	s_add_i32 s8, s12, s8
	s_ashr_i32 s9, s8, 3
	s_and_b32 s8, s8, -8
	s_sub_i32 s8, s12, s8
	s_cmp_lt_i32 s8, 0
	s_movk_i32 s10, 0x161
	s_cselect_b32 s10, s10, 0x160
	s_mul_i32 s8, s8, s10
	s_add_i32 s8, s8, s9
	s_mul_hi_i32 s9, s8, 0x2e8ba2e9
	s_lshr_b32 s10, s9, 31
	s_ashr_i32 s9, s9, 5
	s_add_i32 s9, s9, s10
	s_lshl_b32 s10, s9, 3
	s_mulk_i32 s9, 0xb0
	s_sub_i32 s9, s8, s9
	s_lshr_b32 s8, s9, 3
	s_and_b32 s9, s9, 7
	s_add_i32 s10, s10, s9
